# nt streaming hint on more read-once full-line loads: attn_merge group-output loads (not the shared LSE lines) and hgrn_sample recurrent-state loads; on top of nt P9 K/V/Q and hgrn_scan SL loads
# speedup vs baseline: 1.0123x; 1.0123x over previous
; __device__ __forceinline__ float bf2f(unsigned short x) { return __uint_as_float((unsigned)x << 16); }
; __device__ __forceinline__ float fast_exp(float x) { return __builtin_amdgcn_exp2f(x * LOG2E); }
; __device__ __forceinline__ void hgrn_sample(Frame& F, float* rso) {
;     ...
;     for (int it = F.bid; it < 256; it += F.G) {
;         const int b = it >> 3, h = it & 7;
;         __syncthreads();
;         for (int e = tid; e < 1024; e += 512) { const int t = e >> 7, c = e & 127; const size_t off = wt_off(MP + b * 8 + t, h * 128 + c, DM);
;             qs[e] = bf2f(QH[off]); fs[e] = fast_exp(bf2f(LOGF[off])); vs[e] = bf2f(VH[off]); gs[e] = bf2f(GH[off]); }
;         float S[32];
;         const size_t sb = ((size_t)it * 128 + 32 * kq) * 128 + v;
; #pragma unroll
;         for (int i = 0; i < 32; ++i) S[i] = S0[sb + (size_t)i * 128];
;         __syncthreads();
.LBB0_680:
	s_or_b64 exec, exec, s[4:5]
	s_ashr_i32 s19, s18, 31
	s_lshl_b64 s[4:5], s[18:19], 14
	v_lshl_add_u64 v[6:7], v[2:3], 0, s[4:5]
	v_lshl_add_u64 v[16:17], v[6:7], 2, s[12:13]
	v_add_co_u32_e32 v18, vcc, 0x1000, v16
	global_load_dword v14, v[16:17], off nt
	global_load_dword v15, v[16:17], off offset:512 nt
	global_load_dword v12, v[16:17], off offset:1024 nt
	global_load_dword v13, v[16:17], off offset:1536 nt
	global_load_dword v10, v[16:17], off offset:2048 nt
	global_load_dword v11, v[16:17], off offset:2560 nt
	global_load_dword v8, v[16:17], off offset:3072 nt
	global_load_dword v9, v[16:17], off offset:3584 nt
	v_addc_co_u32_e32 v19, vcc, 0, v17, vcc
	global_load_dword v36, v[18:19], off nt
	global_load_dword v37, v[18:19], off offset:512 nt
	global_load_dword v34, v[18:19], off offset:1024 nt
	global_load_dword v35, v[18:19], off offset:1536 nt
	global_load_dword v32, v[18:19], off offset:2048 nt
	global_load_dword v33, v[18:19], off offset:2560 nt
	global_load_dword v30, v[18:19], off offset:3072 nt
	global_load_dword v31, v[18:19], off offset:3584 nt
	v_add_co_u32_e32 v18, vcc, 0x2000, v16
	s_mov_b32 s4, 0
	s_nop 0
	v_addc_co_u32_e32 v19, vcc, 0, v17, vcc
	v_add_co_u32_e32 v40, vcc, 0x3000, v16
	global_load_dword v28, v[18:19], off nt
	global_load_dword v29, v[18:19], off offset:512 nt
	global_load_dword v26, v[18:19], off offset:1024 nt
	global_load_dword v27, v[18:19], off offset:1536 nt
	global_load_dword v24, v[18:19], off offset:2048 nt
	global_load_dword v25, v[18:19], off offset:2560 nt
	global_load_dword v22, v[18:19], off offset:3072 nt
	global_load_dword v23, v[18:19], off offset:3584 nt
	v_addc_co_u32_e32 v41, vcc, 0, v17, vcc
	global_load_dword v20, v[40:41], off nt
	global_load_dword v21, v[40:41], off offset:512 nt
	global_load_dword v18, v[40:41], off offset:1024 nt
	global_load_dword v19, v[40:41], off offset:1536 nt
	global_load_dword v16, v[40:41], off offset:2048 nt
	global_load_dword v17, v[40:41], off offset:2560 nt
	global_load_dword v38, v[40:41], off offset:3072 nt
	s_nop 0
	global_load_dword v40, v[40:41], off offset:3584 nt
	v_mov_b32_e32 v4, v57
	s_waitcnt lgkmcnt(0)
	s_barrier

; #define GAS __attribute__((address_space(1)))
; __device__ __forceinline__ unsigned pk2(float lo, float hi) { f32x2 v = {lo, hi}; bf16x2_t b = __builtin_convertvector(v, bf16x2_t); return __builtin_bit_cast(unsigned, b); }
; __device__ __forceinline__ float bflo(unsigned w) { return __uint_as_float(w << 16); }
; __device__ __forceinline__ float bfhi(unsigned w) { return __uint_as_float(w & 0xffff0000u); }
; __device__ __forceinline__ void attn_merge(Frame& F) {
;     ...
;     for (int idx = F.bid * 512 + F.tid; idx < MT * 128; idx += F.G * 512) {
;         const int row = idx >> 7, c8 = idx & 127, h = c8 >> 3;
;         const float l0 = LSE[((size_t)0 * MT + row) * 16 + h], l1 = LSE[((size_t)1 * MT + row) * 16 + h], l2 = LSE[((size_t)2 * MT + row) * 16 + h];
;         const float mx = fmaxf(l0, fmaxf(l1, l2)); const float e0 = __expf(l0 - mx), e1 = __expf(l1 - mx), e2 = __expf(l2 - mx); const float inv = 1.f / (e0 + e1 + e2);
;         const float wgt[3] = {e0 * inv, e1 * inv, e2 * inv};
;         float acc[8] = {0.f, 0.f, 0.f, 0.f, 0.f, 0.f, 0.f, 0.f};
; #pragma unroll
;         for (int gi = 0; gi < 3; ++gi) { const v4u x = *(const GAS v4u*)((const bf16*)(F.ws + WS_OG + (size_t)gi * QKV_STRIDE) + (size_t)row * DM + c8 * 8);
;             acc[0] += wgt[gi] * bflo(x.x); acc[1] += wgt[gi] * bfhi(x.x); acc[2] += wgt[gi] * bflo(x.y); acc[3] += wgt[gi] * bfhi(x.y);
;             acc[4] += wgt[gi] * bflo(x.z); acc[5] += wgt[gi] * bfhi(x.z); acc[6] += wgt[gi] * bflo(x.w); acc[7] += wgt[gi] * bfhi(x.w); }
;         *(GAS v4u*)(OM + wt_off(row, c8 * 8, DM)) = (v4u){pk2(acc[0], acc[1]), pk2(acc[2], acc[3]), pk2(acc[4], acc[5]), pk2(acc[6], acc[7])};
;     }
.LBB0_1748:
	v_ashrrev_i32_e32 v12, 7, v10
	v_ashrrev_i32_e32 v13, 31, v12
	v_lshrrev_b32_e32 v19, 3, v12
	v_lshlrev_b32_e32 v24, 6, v12
	v_lshlrev_b32_e32 v36, 2, v12
	v_lshlrev_b64 v[16:17], 6, v[12:13]
	v_lshlrev_b64 v[12:13], 11, v[12:13]
	v_lshl_add_u64 v[28:29], v[4:5], 0, v[12:13]
	v_ashrrev_i32_e32 v14, 15, v10
	v_add_co_u32_e32 v12, vcc, s12, v28
	v_ashrrev_i32_e32 v15, 31, v14
	s_nop 0
	v_addc_co_u32_e32 v13, vcc, 0, v29, vcc
	v_lshlrev_b64 v[26:27], 19, v[14:15]
	v_lshl_add_u64 v[14:15], s[8:9], 0, v[16:17]
	v_add_co_u32_e32 v30, vcc, s13, v28
	v_lshl_add_u64 v[16:17], v[14:15], 0, v[8:9]
	s_nop 0
	v_addc_co_u32_e32 v31, vcc, 0, v29, vcc
	v_add_co_u32_e32 v32, vcc, 0x104000, v16
	global_load_dword v38, v[16:17], off
	s_nop 0
	v_addc_co_u32_e32 v33, vcc, 0, v17, vcc
	v_bfe_u32 v18, v10, 2, 1
	v_add_co_u32_e32 v34, vcc, 0x208000, v16
	v_and_or_b32 v37, v19, 14, v18
	global_load_dwordx4 v[12:15], v[12:13], off nt
	v_addc_co_u32_e32 v35, vcc, 0, v17, vcc
	global_load_dword v39, v[32:33], off
	global_load_dword v40, v[34:35], off
	global_load_dwordx4 v[16:19], v[28:29], off nt
	global_load_dwordx4 v[20:23], v[30:31], off nt
	v_and_b32_e32 v2, 0x4000, v10
	v_lshl_add_u64 v[26:27], v[6:7], 0, v[26:27]
	v_lshl_add_u64 v[26:27], v[26:27], 0, v[2:3]
	v_add_u32_e32 v10, s3, v10
	v_cmp_lt_i32_e64 s[0:1], s15, v10
	s_or_b64 s[10:11], s[0:1], s[10:11]
	v_and_or_b32 v24, v24, s14, v11
	v_and_b32_e32 v28, 32, v36
	v_lshlrev_b32_e32 v29, 10, v37
	v_mov_b32_e32 v25, v3
	v_bitop3_b32 v24, v24, v29, v28 bitop3:0xde
	v_lshl_add_u64 v[24:25], v[26:27], 0, v[24:25]
	s_waitcnt vmcnt(4)
	v_lshlrev_b32_e32 v26, 16, v12
	s_waitcnt vmcnt(2)
	v_max3_f32 v2, v38, v39, v40
	v_sub_f32_e32 v38, v38, v2
	v_sub_f32_e32 v39, v39, v2
	v_sub_f32_e32 v2, v40, v2
	v_mul_f32_e32 v38, 0x3fb8aa3b, v38
	v_mul_f32_e32 v39, 0x3fb8aa3b, v39
	v_mul_f32_e32 v2, 0x3fb8aa3b, v2
	v_exp_f32_e32 v38, v38
	v_exp_f32_e32 v39, v39
	v_exp_f32_e32 v40, v2
	s_waitcnt vmcnt(1)
	v_lshlrev_b32_e32 v34, 16, v16
	v_and_b32_e32 v35, 0xffff0000, v16
	v_add_f32_e32 v2, v38, v39
	v_add_f32_e32 v2, v40, v2
	v_div_scale_f32 v41, s[0:1], v2, v2, 1.0
	v_rcp_f32_e32 v43, v41
	v_div_scale_f32 v42, vcc, 1.0, v2, 1.0
	v_lshlrev_b32_e32 v16, 16, v17
	v_fma_f32 v44, -v41, v43, 1.0
	v_fmac_f32_e32 v43, v44, v43
	v_mul_f32_e32 v44, v42, v43
	v_fma_f32 v45, -v41, v44, v42
	v_fmac_f32_e32 v44, v45, v43
	v_fma_f32 v41, -v41, v44, v42
	v_div_fmas_f32 v41, v41, v43, v44
	v_div_fixup_f32 v41, v41, v2, 1.0
	v_and_b32_e32 v17, 0xffff0000, v17
	v_lshlrev_b32_e32 v36, 16, v18
	v_and_b32_e32 v37, 0xffff0000, v18
	v_lshlrev_b32_e32 v18, 16, v19
	v_and_b32_e32 v19, 0xffff0000, v19
	v_mul_f32_e32 v2, v38, v41
	v_and_b32_e32 v27, 0xffff0000, v12
	v_lshlrev_b32_e32 v12, 16, v13
	v_and_b32_e32 v13, 0xffff0000, v13
	v_lshlrev_b32_e32 v30, 16, v14
	v_and_b32_e32 v31, 0xffff0000, v14
	v_lshlrev_b32_e32 v14, 16, v15
	v_and_b32_e32 v15, 0xffff0000, v15
	v_mul_f32_e32 v38, v39, v41
	v_pk_fma_f32 v[34:35], v[2:3], v[34:35], 0 op_sel_hi:[0,1,0]
	v_pk_fma_f32 v[16:17], v[2:3], v[16:17], 0 op_sel_hi:[0,1,0]
	v_pk_fma_f32 v[36:37], v[2:3], v[36:37], 0 op_sel_hi:[0,1,0]
	v_pk_fma_f32 v[18:19], v[2:3], v[18:19], 0 op_sel_hi:[0,1,0]
	s_waitcnt vmcnt(0)
	v_lshlrev_b32_e32 v28, 16, v20
	v_and_b32_e32 v29, 0xffff0000, v20
	v_lshlrev_b32_e32 v20, 16, v21
	v_and_b32_e32 v21, 0xffff0000, v21
	v_lshlrev_b32_e32 v32, 16, v22
	v_and_b32_e32 v33, 0xffff0000, v22
	v_lshlrev_b32_e32 v22, 16, v23
	v_and_b32_e32 v23, 0xffff0000, v23
	v_mul_f32_e32 v40, v40, v41
	v_pk_fma_f32 v[26:27], v[38:39], v[26:27], v[34:35] op_sel_hi:[0,1,1]
	v_pk_fma_f32 v[12:13], v[38:39], v[12:13], v[16:17] op_sel_hi:[0,1,1]
	v_pk_fma_f32 v[16:17], v[38:39], v[30:31], v[36:37] op_sel_hi:[0,1,1]
	v_pk_fma_f32 v[14:15], v[38:39], v[14:15], v[18:19] op_sel_hi:[0,1,1]
	v_pk_fma_f32 v[18:19], v[40:41], v[28:29], v[26:27] op_sel_hi:[0,1,1]
	v_pk_fma_f32 v[20:21], v[40:41], v[20:21], v[12:13] op_sel_hi:[0,1,1]
	v_pk_fma_f32 v[16:17], v[40:41], v[32:33], v[16:17] op_sel_hi:[0,1,1]
	v_pk_fma_f32 v[22:23], v[40:41], v[22:23], v[14:15] op_sel_hi:[0,1,1]
	v_cvt_pk_bf16_f32 v12, v18, v19
	v_cvt_pk_bf16_f32 v13, v20, v21
	v_cvt_pk_bf16_f32 v14, v16, v17
	v_cvt_pk_bf16_f32 v15, v22, v23
	global_store_dwordx4 v[24:25], v[12:15], off
	s_andn2_b64 exec, exec, s[10:11]
	s_cbranch_execnz .LBB0_1748
